# v54 + RWKV state image written as packed dwords (DPP column-pair exchange, 4 ds_write_b32 instead of 8 ds_write_b16)
# speedup vs baseline: 1.0131x; 1.0004x over previous
; #define LAS __attribute__((address_space(3)))
; __device__ __forceinline__ bf16_t f2bf(float f) { const __bf16 r = (__bf16)f; bf16_t u; __builtin_memcpy(&u, &r, 2); return u; }
; __device__ __forceinline__ f32x4 mfma16(bf16x8 a, bf16x8 b, f32x4 c) { return __builtin_amdgcn_mfma_f32_16x16x32_bf16(a, b, c, 0, 0, 0); }
; __device__ __forceinline__ void rwkv_chunk_item(const P& p, const Ctx& c, int seg, int w, bool save) {
;     ...
;     auto simg = [&](int l15, int quad) {
; #pragma unroll
;         for (int x = 0; x < 2; ++x) { const int ti = c.wv * 2 + x, mt = ti >> 2, nt = ti & 3;
; #pragma unroll
;             for (int jj = 0; jj < 4; ++jj) S0I[(mt * 16 + quad * 4 + jj) * 72 + nt * 16 + l15] = f2bf(S[x][jj]); } };
;     ...
; #pragma unroll
;         for (int x = 0; x < 2; ++x) { const int ti = c.wv * 2 + x, mt = ti >> 2, nt = ti & 3;
;             S[x] = mfma16(*(const LAS bf16x8*)(UV + (mt * 16 + l15) * 40 + quad * 8), *(const LAS bf16x8*)(EBT + (nt * 16 + l15) * 40 + quad * 8), S[x]);
;             const float gt = GT[nt * 16 + l15];
; #pragma unroll
;             for (int jj = 0; jj < 4; ++jj) S[x][jj] *= gt; }
;         simg(l15, quad);
;         if (c.wv < 4 && ch + 1 < SEGT / 16) gtile(pb ^ 1, l15, quad);
.LBB0_900:
	v_add_u32_e32 v22, s45, v82
	v_lshl_add_u32 v2, v45, 1, s88
	v_mad_u64_u32 v[22:23], s[2:3], v22, s64, v[2:3]
	ds_read_b128 v[22:25], v22 offset:14336
	v_add_u32_e32 v42, s34, v82
	v_mad_u64_u32 v[38:39], s[2:3], v42, s64, v[2:3]
	ds_read_b128 v[38:41], v38 offset:9216
	v_add_u32_e32 v124, s66, v82
	v_mad_u64_u32 v[124:125], s[2:3], v124, s64, v[2:3]
	ds_read_b128 v[124:127], v124 offset:9216
	v_lshl_add_u32 v128, v42, 2, s88
	v_add_u32_e32 v128, 0x5800, v128
	ds_read2_b32 v[42:43], v128 offset0:192 offset1:208
	s_waitcnt lgkmcnt(2)
	v_mfma_f32_16x16x32_bf16 v[6:9], v[22:25], v[38:41], v[6:9]
	s_waitcnt lgkmcnt(0)
	v_mfma_f32_16x16x32_bf16 v[10:13], v[22:25], v[124:127], v[10:13]
	v_mov_b32_e32 v2, v43
	v_lshlrev_b32_e32 v38, 2, v83
	s_nop 7
	v_pk_mul_f32 v[6:7], v[42:43], v[6:7] op_sel_hi:[0,1]
	s_nop 4
	v_pk_mul_f32 v[10:11], v[2:3], v[10:11] op_sel_hi:[0,1]
	v_pk_mul_f32 v[12:13], v[2:3], v[12:13] op_sel_hi:[0,1]
	v_add_u32_e32 v2, s45, v38
	v_lshlrev_b32_e32 v22, 1, v82
	v_mul_lo_u32 v2, v2, s63
	v_pk_mul_f32 v[8:9], v[42:43], v[8:9] op_sel_hi:[0,1]
	v_add3_u32 v2, s40, v22, v2
	v_and_b32_e32 v140, 1, v82
	v_cmp_ne_u32_e64 s[2:3], 0, v140
	v_mov_b32_e32 v141, 0x5040100
	v_mov_b32_e32 v142, 0x3020706
	v_mul_u32_u24_e32 v140, 0x11e, v140
	v_cndmask_b32_e64 v141, v141, v142, s[2:3]
	v_add_u32_e32 v140, v2, v140
	v_cvt_pk_bf16_f32 v22, v6, v8
	v_cvt_pk_bf16_f32 v23, v7, v9
	v_cvt_pk_bf16_f32 v142, v10, v12
	v_cvt_pk_bf16_f32 v143, v11, v13
	v_mov_b32_dpp v144, v22 quad_perm:[1,0,3,2] row_mask:0xf bank_mask:0xf bound_ctrl:1
	v_mov_b32_dpp v145, v23 quad_perm:[1,0,3,2] row_mask:0xf bank_mask:0xf bound_ctrl:1
	v_mov_b32_dpp v146, v142 quad_perm:[1,0,3,2] row_mask:0xf bank_mask:0xf bound_ctrl:1
	v_mov_b32_dpp v147, v143 quad_perm:[1,0,3,2] row_mask:0xf bank_mask:0xf bound_ctrl:1
	v_perm_b32 v22, v144, v22, v141
	v_perm_b32 v23, v145, v23, v141
	v_perm_b32 v142, v146, v142, v141
	v_perm_b32 v143, v147, v143, v141
	s_or_b64 s[2:3], s[56:57], s[4:5]
	ds_write_b32 v140, v22 offset:47104
	ds_write_b32 v140, v23 offset:47248
	ds_write_b32 v140, v142 offset:47136
	s_and_b64 vcc, exec, s[2:3]
	ds_write_b32 v140, v143 offset:47280
	s_cbranch_vccnz .LBB0_929
	s_xor_b32 s2, s87, 1
	s_mulk_i32 s2, 0x5c00
	v_add_u32_e32 v2, s67, v82
	s_add_i32 s4, s2, 0
	v_mul_lo_u32 v2, v2, s63
	v_lshlrev_b32_e32 v22, 1, v45
	v_add_u32_e32 v23, s83, v82
	v_add3_u32 v2, s4, v2, v22
	v_mul_lo_u32 v23, v23, s63
	v_add3_u32 v39, s4, v23, v22
	ds_read_b128 v[22:25], v2 offset:4608
	ds_read_b128 v[40:43], v39
	ds_read_b128 v[124:127], v2 offset:4672
	ds_read_b128 v[86:89], v39 offset:64
	s_waitcnt lgkmcnt(2)
	v_mfma_f32_16x16x32_bf16 v[22:25], v[22:25], v[40:43], 0
	v_add_u32_e32 v39, s4, v84
	v_add_u32_e32 v2, s84, v39
	s_waitcnt lgkmcnt(0)
	v_mfma_f32_16x16x32_bf16 v[22:25], v[124:127], v[86:89], v[22:25]
	s_mov_b64 s[2:3], -1
	s_and_b64 vcc, exec, s[72:73]
	v_lshl_add_u32 v40, v38, 1, v2
	s_cbranch_vccz .LBB0_903
	s_nop 3
	v_cvt_pk_bf16_f32 v2, v22, s0
	v_cmp_le_i32_e32 vcc, v38, v82
	s_mov_b64 s[2:3], 0
	s_nop 0
	v_cndmask_b32_e32 v2, 0, v2, vcc
	ds_write_b16 v40, v2 offset:20736
